# removed the redundant start-of-kernel cooperative grid sync (nothing is published before phase 0; phase seams use the XCD barrier)
# speedup vs baseline: 1.0860x; 1.0019x over previous
; #define PG8_LAS __attribute__((address_space(3)))
; #define LAS __attribute__((address_space(3)))
; __device__ __forceinline__ unsigned xb_ld(unsigned* p)              { return __hip_atomic_load(p, __ATOMIC_RELAXED, __HIP_MEMORY_SCOPE_AGENT); }
; __device__ __forceinline__ void xcd_barrier_complete(unsigned* bar, unsigned x, unsigned& nloc, unsigned& nx) {
;     const unsigned G = gridDim.x * gridDim.y * gridDim.z;
;     unsigned sum, cnt, mine, sp = 0u;
;     for (;;) {
;         sum = 0u; cnt = 0u; mine = 0u;
; #pragma unroll
;         for (unsigned j = 0; j < 16; ++j) { const unsigned c = xb_ld(&bar[XB_XCNT(j)]); sum += c; cnt += (c > 0u) ? 1u : 0u; mine = (j == x) ? c : mine; }
; __global__ void __launch_bounds__(512, 2) fwd_mega(Args a_) {
;     ...
;     cg::grid_group grid = cg::this_grid();
;     PG8_LAS float* edge = (PG8_LAS float*)((PG8_LAS unsigned char*)lds + RING_BYTES);
;     volatile LAS unsigned* bst = (volatile LAS unsigned*)((LAS unsigned char*)lds + LDS_BYTES - 16);
;     const int wave_s = __builtin_amdgcn_readfirstlane(threadIdx.x >> 6);
;     if (threadIdx.x < 4) bst[threadIdx.x] = 0u;
;     __syncthreads();
;     XcdBarrier xbar = xcd_barrier_post((unsigned*)(ap0->ws + WS_BAR), bst);
;     grid.sync();
.LBB0_5:
	s_or_b64 exec, exec, s[6:7]
	v_lshrrev_b32_e32 v2, 20, v0
	v_lshrrev_b32_e32 v0, 10, v0
	v_or_b32_e32 v0, v0, v2
	s_movk_i32 s6, 0x3ff
	v_and_or_b32 v0, v0, s6, v1
	v_cmp_eq_u32_e32 vcc, 0, v0
	s_barrier
	s_and_b32 s84, s3, 0xffffffc0
	s_cmpk_lt_i32 s96, 0x104
	s_cselect_b64 s[6:7], -1, 0
	s_ashr_i32 s97, s96, 31
	s_lshr_b32 s3, s97, 29
	s_add_i32 s3, s96, s3
	s_ashr_i32 s85, s3, 3
	s_and_b32 s3, s3, -8
	s_sub_i32 s86, s96, s3
	s_lshl_b32 s3, s86, 5
	s_or_b32 s3, s3, 4
	s_ashr_i32 s87, s94, 31
	s_lshl_b32 s93, s96, 3
	s_lshl_b32 s80, s94, 3
	v_writelane_b32 v253, s6, 0
	s_cmpk_lt_i32 s96, 0x100
	v_mov_b32_e32 v196, 0x358637bd
	v_writelane_b32 v253, s7, 1
	s_cselect_b64 s[6:7], -1, 0
	v_writelane_b32 v253, s6, 2
	s_cmpk_lt_i32 s96, 0xb42
	v_mov_b32_e32 v197, 1
	v_writelane_b32 v253, s7, 3
	s_cselect_b64 s[6:7], -1, 0
	v_writelane_b32 v253, s6, 4
	v_mov_b32_e32 v199, 0x1200
	s_movk_i32 s64, 0x6000
	v_writelane_b32 v253, s7, 5
	s_mul_i32 s6, s86, 0x168
	s_or_b32 s6, s6, 2
	s_cmpk_lt_i32 s96, 0x514
	s_mul_i32 s7, s86, 0xa2
	s_cselect_b64 s[8:9], -1, 0
	s_add_i32 s7, s7, 4
	s_lshl_b32 s14, s96, 9
	s_add_u32 s54, s0, 0xb0200
	s_addc_u32 s55, s1, 0
	s_add_u32 s60, s0, 0xb0400
	s_addc_u32 s61, s1, 0
	s_add_u32 s12, s0, 0xb0500
	s_addc_u32 s13, s1, 0
	s_add_u32 s16, s0, 0xb0600
	s_addc_u32 s17, s1, 0
	s_add_u32 s62, s0, 0xb0700
	v_writelane_b32 v253, s8, 6
	s_addc_u32 s63, s1, 0
	s_mov_b32 s33, 0x800000
	v_writelane_b32 v253, s9, 7
	s_add_u32 s8, s0, 0xb0800
	s_addc_u32 s9, s1, 0
	v_writelane_b32 v253, s8, 8
	s_movk_i32 s82, 0x40ff
	s_movk_i32 s26, 0x407f
	v_writelane_b32 v253, s9, 9
	s_add_u32 s8, s0, 0xb0900
	s_addc_u32 s9, s1, 0
	v_writelane_b32 v253, s8, 10
	s_movk_i32 s27, 0xb00
	s_movk_i32 s90, 0x5800
	v_writelane_b32 v253, s9, 11
	s_add_u32 s8, s0, 0xb0a00
	s_addc_u32 s9, s1, 0
	v_writelane_b32 v253, s8, 12
	s_mov_b32 s83, 0
	s_mov_b32 s25, 0
	v_writelane_b32 v253, s9, 13
	s_add_u32 s8, s0, 0xb0b00
	s_addc_u32 s9, s1, 0
	v_writelane_b32 v253, s8, 14
	s_mov_b64 s[28:29], 0x80
	s_mov_b32 s30, 0xbf1b4598
	v_writelane_b32 v253, s9, 15
	s_add_u32 s8, s0, 0xb0c00
	s_addc_u32 s9, s1, 0
	v_writelane_b32 v253, s8, 16
	s_mov_b64 s[34:35], 0x1200
	s_nop 0
	v_writelane_b32 v253, s9, 17
	s_add_u32 s8, s0, 0xb0d00
	s_addc_u32 s9, s1, 0
	v_writelane_b32 v253, s8, 18
	s_nop 1
	v_writelane_b32 v253, s9, 19
	s_add_u32 s8, s0, 0xb0e00
	s_addc_u32 s9, s1, 0
	v_writelane_b32 v253, s8, 20
	s_nop 1
	v_writelane_b32 v253, s9, 21
	s_add_u32 s8, s0, 0xb0f00
	s_addc_u32 s9, s1, 0
	v_writelane_b32 v253, s8, 22
	s_nop 1
	v_writelane_b32 v253, s9, 23
	s_add_u32 s8, s0, 0xb1000
	s_addc_u32 s9, s1, 0
	v_writelane_b32 v253, s8, 24
	s_nop 1
	v_writelane_b32 v253, s9, 25
	s_add_u32 s8, s0, 0xb1100
	s_addc_u32 s9, s1, 0
	v_writelane_b32 v253, s8, 26
	s_nop 1
	v_writelane_b32 v253, s9, 27
	s_add_u32 s8, s0, 0xb1200
	s_addc_u32 s9, s1, 0
	v_writelane_b32 v253, s8, 28
	s_nop 1
	v_writelane_b32 v253, s9, 29
	s_add_u32 s8, s0, 0xb1300
	s_addc_u32 s9, s1, 0
	v_writelane_b32 v253, s8, 30
	s_cmp_eq_u32 s2, 15
	s_nop 0
	v_writelane_b32 v253, s9, 31
	s_cselect_b64 s[8:9], -1, 0
	v_writelane_b32 v253, s8, 32
	s_cmp_eq_u32 s2, 14
	s_nop 0
	v_writelane_b32 v253, s9, 33
	s_cselect_b64 s[8:9], -1, 0
	v_writelane_b32 v253, s8, 34
	s_cmp_eq_u32 s2, 13
	s_nop 0
	v_writelane_b32 v253, s9, 35
	s_cselect_b64 s[8:9], -1, 0
	v_writelane_b32 v253, s8, 36
	s_cmp_eq_u32 s2, 12
	s_nop 0
	v_writelane_b32 v253, s9, 37
	s_cselect_b64 s[8:9], -1, 0
	v_writelane_b32 v253, s8, 38
	s_cmp_eq_u32 s2, 11
	s_nop 0
	v_writelane_b32 v253, s9, 39
	s_cselect_b64 s[8:9], -1, 0
	v_writelane_b32 v253, s8, 40
	s_cmp_eq_u32 s2, 10
	s_nop 0
	v_writelane_b32 v253, s9, 41
	s_cselect_b64 s[8:9], -1, 0
	v_writelane_b32 v253, s8, 42
	s_cmp_eq_u32 s2, 9
	s_nop 0
	v_writelane_b32 v253, s9, 43
	s_cselect_b64 s[8:9], -1, 0
	v_writelane_b32 v253, s8, 44
	s_cmp_eq_u32 s2, 8
	s_nop 0
	v_writelane_b32 v253, s9, 45
	s_cselect_b64 s[8:9], -1, 0
	v_writelane_b32 v253, s8, 46
	s_cmp_eq_u32 s2, 7
	s_nop 0
	v_writelane_b32 v253, s9, 47
	s_cselect_b64 s[8:9], -1, 0
	v_writelane_b32 v253, s8, 48
	s_cmp_eq_u32 s2, 6
	s_nop 0
	v_writelane_b32 v253, s9, 49
	s_cselect_b64 s[8:9], -1, 0
	v_writelane_b32 v253, s8, 50
	s_cmp_eq_u32 s2, 5
	s_nop 0
	v_writelane_b32 v253, s9, 51
	s_cselect_b64 s[8:9], -1, 0
	v_writelane_b32 v253, s8, 52
	s_cmp_eq_u32 s2, 4
	s_nop 0
	v_writelane_b32 v253, s9, 53
	s_cselect_b64 s[8:9], -1, 0
	v_writelane_b32 v253, s8, 54
	s_cmp_eq_u32 s2, 3
	s_nop 0
	v_writelane_b32 v253, s9, 55
	s_cselect_b64 s[8:9], -1, 0
	v_writelane_b32 v253, s8, 56
	s_cmp_eq_u32 s2, 2
	s_nop 0
	v_writelane_b32 v253, s9, 57
	s_cselect_b64 s[8:9], -1, 0
	v_writelane_b32 v253, s8, 58
	s_cmp_eq_u32 s2, 1
	s_nop 0
	v_writelane_b32 v253, s9, 59
	s_cselect_b64 s[8:9], -1, 0
	v_writelane_b32 v253, s8, 60
	s_cmp_eq_u32 s2, 0
	s_nop 0
	v_writelane_b32 v253, s9, 61
	s_cselect_b64 s[8:9], -1, 0
	s_lshl_b32 s2, s2, 8
	s_add_u32 s2, s4, s2
	v_writelane_b32 v253, s8, 62
	s_addc_u32 s4, s5, 0
	s_nop 0
	v_writelane_b32 v253, s9, 63
	s_add_u32 s8, s2, 0x1400
	s_addc_u32 s9, s4, 0
	v_writelane_b32 v254, s8, 0
	s_nop 1
	v_writelane_b32 v254, s9, 1
	s_add_u32 s8, s2, 0x2400
	s_addc_u32 s9, s4, 0
	v_writelane_b32 v254, s8, 2
	s_add_u32 s4, s0, 0xb3400
	s_addc_u32 s5, s1, 0
	v_writelane_b32 v254, s9, 3
	v_writelane_b32 v254, s4, 4
	s_add_u32 s0, s0, 0xb3500
	s_addc_u32 s1, s1, 0
	v_writelane_b32 v254, s5, 5
;     __host__ __device__ bool next(int i, Unit& u) const {
;         const long L = (long)i * G + c; if (L >= nwg) return false;
;         int wgid = (int)L; { const int q = nwg / NXCD, r = nwg % NXCD, xcd = wgid % NXCD, off = wgid / NXCD; wgid = (xcd < r ? xcd * (q + 1) : r * (q + 1) + (xcd - r) * q) + off; }
;         const int nig = WGM * nN, gid = wgid / nig, fm = gid * WGM, gsz = (nM - fm) < WGM ? (nM - fm) : WGM;
;         u.pm = fm + ((wgid % nig) % gsz); u.pn = (wgid % nig) / gsz; return true;
; __device__ __forceinline__ void xcd_barrier_complete(unsigned* bar, unsigned x, unsigned& nloc, unsigned& nx) {
;     const unsigned G = gridDim.x * gridDim.y * gridDim.z;
	v_writelane_b32 v254, s0, 6
	s_cmp_lt_i32 s86, 4
	s_nop 0
	v_writelane_b32 v254, s1, 7
	s_mul_i32 s0, s86, 33
	s_cselect_b32 s0, s0, s3
	s_mul_i32 s1, s86, 0xa3
	s_cselect_b32 s1, s1, s7
	s_add_i32 s0, s0, s85
	s_ashr_i32 s2, s0, 31
	s_lshr_b32 s2, s2, 27
	s_add_i32 s2, s0, s2
	s_and_b32 s3, s2, 0xffffffe0
	s_sub_i32 s3, s0, s3
	s_ashr_i32 s0, s2, 5
	s_lshl_b32 s2, s0, 3
	s_sub_i32 s0, 0x41, s2
	s_min_u32 s4, s0, 8
	s_cmp_lt_i32 s86, 2
	s_mul_i32 s0, s86, 0x169
	s_cselect_b32 s0, s0, s6
	s_add_i32 s0, s0, s85
	s_mul_hi_i32 s5, s0, 0x2e8ba2e9
	s_lshr_b32 s6, s5, 31
	s_ashr_i32 s5, s5, 5
	s_add_i32 s5, s5, s6
	v_cvt_f32_ubyte0_e32 v1, s4
	s_mul_i32 s6, s5, 0xb0
	s_add_i32 s1, s1, s85
	v_cvt_f32_i32_e32 v0, s3
	v_rcp_iflag_f32_e32 v2, v1
	s_sub_i32 s6, s0, s6
	s_mul_hi_i32 s0, s1, 0x66666667
	s_lshr_b32 s7, s0, 31
	s_ashr_i32 s0, s0, 6
	s_add_i32 s0, s0, s7
	s_lshl_b32 s9, s0, 3
	v_mul_f32_e32 v2, v0, v2
	s_mul_i32 s7, s0, 0xa0
	s_lshl_b32 s5, s5, 3
	s_sub_i32 s0, 0x41, s9
	v_trunc_f32_e32 v2, v2
	s_sub_i32 s7, s1, s7
	s_sub_i32 s1, 0x83, s5
	s_min_u32 s10, s0, 8
	s_ashr_i32 s0, s3, 30
	v_fma_f32 v0, -v2, v1, v0
	s_min_u32 s8, s1, 8
	s_or_b32 s11, s0, 1
	v_cmp_ge_f32_e64 s[0:1], |v0|, v1
	v_cvt_i32_f32_e32 v0, v2
	s_and_b64 s[0:1], s[0:1], exec
	s_cselect_b32 s0, s11, 0
	v_cvt_f32_ubyte0_e32 v1, s8
	v_readfirstlane_b32 s1, v0
	s_add_i32 s0, s1, s0
	s_mul_i32 s1, s0, s4
	v_cvt_f32_i32_e32 v0, s6
	v_rcp_iflag_f32_e32 v2, v1
	s_sub_i32 s1, s3, s1
	s_sext_i32_i8 s1, s1
	s_add_i32 s1, s2, s1
	s_sext_i32_i8 s3, s0
	s_ashr_i32 s0, s6, 30
	s_or_b32 s2, s0, 1
	v_mul_f32_e32 v2, v0, v2
	v_writelane_b32 v254, s1, 8
	s_ashr_i32 s0, s1, 31
	v_trunc_f32_e32 v2, v2
	v_writelane_b32 v254, s0, 9
	v_fma_f32 v0, -v2, v1, v0
	v_writelane_b32 v254, s3, 10
	s_ashr_i32 s0, s3, 31
	v_writelane_b32 v254, s0, 11
	v_cmp_ge_f32_e64 s[0:1], |v0|, v1
	v_cvt_i32_f32_e32 v0, v2
	s_and_b64 s[0:1], s[0:1], exec
	v_cvt_f32_ubyte0_e32 v1, s10
	s_cselect_b32 s0, s2, 0
	v_readfirstlane_b32 s1, v0
	v_cvt_f32_i32_e32 v0, s7
	v_rcp_iflag_f32_e32 v2, v1
	s_add_i32 s2, s1, s0
	s_mul_i32 s0, s2, s8
	s_sub_i32 s0, s6, s0
	s_sext_i32_i16 s0, s0
	v_mul_f32_e32 v2, v0, v2
	s_add_i32 s0, s5, s0
	v_trunc_f32_e32 v2, v2
	v_writelane_b32 v254, s0, 12
	s_ashr_i32 s0, s7, 30
	v_fma_f32 v0, -v2, v1, v0
	s_or_b32 s3, s0, 1
	v_cmp_ge_f32_e64 s[0:1], |v0|, v1
	s_and_b64 s[0:1], s[0:1], exec
	s_load_dword s1, s[78:79], 0x118
	v_cvt_i32_f32_e32 v0, v2
	s_mul_i32 s0, s95, s94
	s_mov_b32 s95, s14
	v_mov_b32_e32 v1, 0
	s_waitcnt lgkmcnt(0)
	s_mul_i32 s91, s0, s1
	s_cselect_b32 s0, s3, 0
	v_readfirstlane_b32 s1, v0
	s_add_i32 s0, s1, s0
	s_mul_i32 s1, s0, s10
	s_sub_i32 s1, s7, s1
	s_sext_i32_i16 s1, s1
	s_add_i32 s1, s9, s1
	v_writelane_b32 v254, s1, 13
	s_sext_i32_i16 s1, s2
	v_writelane_b32 v254, s1, 14
	s_sext_i32_i16 s0, s0
	v_writelane_b32 v254, s0, 15
	s_lshl_b32 s0, s96, 4
	v_writelane_b32 v254, s0, 16
	s_lshl_b32 s0, s96, 8
	v_writelane_b32 v254, s0, 17
	s_add_i32 s0, s93, 0xffffcc80
	v_writelane_b32 v254, s0, 18
	s_add_i32 s0, s93, 0xffffcd00
	v_writelane_b32 v254, s0, 19
	s_add_i32 s0, s93, 0xffffd300
	v_writelane_b32 v254, s0, 20
	s_add_i32 s0, s93, 0xffff7ec0
	v_writelane_b32 v254, s0, 21
	s_add_i32 s0, 0, 0x1c400
	v_writelane_b32 v254, s0, 22
	s_add_i32 s0, 0, 0x1d000
	v_writelane_b32 v254, s0, 23
	s_add_i32 s0, 0, 0x1ce00
	v_writelane_b32 v254, s0, 24
	s_add_i32 s0, 0, 0x1cc00
	v_writelane_b32 v254, s0, 25
	s_add_i32 s0, 0, 0x21d00
	v_writelane_b32 v254, s0, 26
	s_add_i32 s0, 0, 0x16800
	v_writelane_b32 v254, s0, 27
	s_add_i32 s0, 0, 0x14400
	v_writelane_b32 v254, s0, 28
	s_add_i32 s0, 0, 0x18c00
	v_writelane_b32 v254, s0, 29
	s_add_i32 s0, 0, 0x1b000
	v_writelane_b32 v254, s0, 30
	s_add_i32 s0, 0, 0x1d400
	v_writelane_b32 v254, s0, 31
	s_add_i32 s0, 0, 0x1f800
	v_writelane_b32 v254, s0, 32
	s_add_i32 s0, 0, 0x1a800
	v_writelane_b32 v254, s0, 33
	s_add_i32 s0, 0, 0x21c00
	v_writelane_b32 v254, s0, 34
	s_add_i32 s0, 0, 0x20800
	v_writelane_b32 v254, s0, 35
	s_add_i32 s0, 0, 0x20000
	v_writelane_b32 v254, s0, 36
	s_add_i32 s0, 0, 0x13c00
	v_writelane_b32 v254, s0, 37
	s_add_i32 s0, 0, 0x23ff0
	s_ashr_i32 s81, s80, 31
	v_writelane_b32 v254, s0, 38
	s_add_i32 s0, 0, 0x23ff4
	v_writelane_b32 v254, s0, 39
	s_lshl_b64 s[0:1], s[80:81], 6
	v_writelane_b32 v254, s0, 40
	v_writelane_b32 v255, s91, 0
	v_writelane_b32 v255, s12, 1
	v_writelane_b32 v254, s1, 41
	s_lshl_b64 s[0:1], s[80:81], 11
	v_writelane_b32 v254, s0, 42
	v_writelane_b32 v255, s13, 2
	v_mbcnt_lo_u32_b32 v0, -1, 0
	v_writelane_b32 v254, s1, 43
	s_lshl_b64 s[0:1], s[80:81], 12
	v_writelane_b32 v254, s0, 44
	v_writelane_b32 v255, s16, 3
	v_mbcnt_hi_u32_b32 v198, -1, v0
	v_writelane_b32 v254, s1, 45
	v_writelane_b32 v254, s78, 46
	s_mov_b32 s0, s94
	s_movk_i32 s3, 0x400
	v_writelane_b32 v254, s79, 47
	v_writelane_b32 v254, s0, 48
	s_movk_i32 s14, 0x203f
	v_writelane_b32 v255, s17, 4
	v_writelane_b32 v254, s1, 49
	v_writelane_b32 v254, s84, 50
	v_writelane_b32 v254, s85, 51
	v_writelane_b32 v254, s86, 52
	v_writelane_b32 v254, s87, 53
	v_writelane_b32 v254, s93, 54
	v_writelane_b32 v254, s80, 55
	s_barrier
	s_nop 0
	v_writelane_b32 v254, s81, 56
	v_writelane_b32 v254, s95, 57
	v_writelane_b32 v254, s54, 58
	s_nop 1
	v_writelane_b32 v254, s55, 59
	v_writelane_b32 v254, s60, 60
	s_nop 1
	v_writelane_b32 v254, s61, 61
	v_writelane_b32 v254, s62, 62
	s_nop 1
	v_writelane_b32 v254, s63, 63
	s_branch .LBB0_19
